# prologue adaLN GEMV: one L2 touch per 8-row step for the step after next (in-bounds, clamped), static vmcnt counts +1
# baseline (speedup 1.0000x reference)
.LBB0_771:
	s_mul_hi_i32 s2, s12, 0x38e38e39
	s_lshr_b32 s3, s2, 31
	s_ashr_i32 s2, s2, 4
	s_add_i32 s6, s2, s3
	s_mul_i32 s2, s6, 0x48
	s_sub_i32 s2, s12, s2
	s_ashr_i32 s7, s6, 31
	s_lshl_b32 s2, s2, 7
	s_lshl_b64 s[8:9], s[6:7], 10
	s_add_u32 s3, s8, s1
	s_addc_u32 s7, s9, s4
	s_mul_i32 s7, s7, 0x9000
	s_mul_hi_u32 s8, s3, 0x9000
	s_add_i32 s8, s8, s7
	s_mul_i32 s3, s3, 0x9000
	s_add_u32 s7, s50, s3
	s_addc_u32 s10, s51, s8
	s_ashr_i32 s3, s2, 31
	s_lshl_b64 s[8:9], s[2:3], 2
	s_add_u32 s2, s7, s8
	s_addc_u32 s3, s10, s9
	v_mov_b32_e32 v8, 0
	v_lshl_add_u64 v[6:7], s[2:3], 0, v[128:129]
	v_and_b32_e32 v158, 63, v191
	v_lshrrev_b32_e32 v159, 3, v158
	v_and_b32_e32 v158, 7, v158
	v_mul_u32_u24_e32 v159, 0x9000, v159
	v_lshl_add_u32 v158, v158, 6, v159
	v_mov_b32_e32 v159, 0
	v_lshl_add_u64 v[160:161], s[2:3], 0, v[158:159]
	s_mov_b64 s[10:11], 0
	s_mov_b32 s7, s5
	v_mov_b32_e32 v9, v8
	v_mov_b32_e32 v10, v8
	v_mov_b32_e32 v11, v8
	v_mov_b32_e32 v12, v8
	v_mov_b32_e32 v13, v8
	v_mov_b32_e32 v14, v8
	v_mov_b32_e32 v15, v8
	v_mov_b32_e32 v16, v8
	v_mov_b32_e32 v17, v8
	v_mov_b32_e32 v18, v8
	v_mov_b32_e32 v19, v8
	v_mov_b32_e32 v20, v8
	v_mov_b32_e32 v21, v8
	v_mov_b32_e32 v22, v8
	v_mov_b32_e32 v23, v8
	v_mov_b32_e32 v24, v8
	v_mov_b32_e32 v25, v8
.LBB0_772:
	v_lshl_add_u64 v[26:27], v[6:7], 0, s[10:11]
	v_add_co_u32_e64 v104, s[2:3], s70, v26
	global_load_dwordx2 v[94:95], v[26:27], off
	s_nop 0
	v_addc_co_u32_e64 v105, s[2:3], 0, v27, s[2:3]
	s_mov_b32 s2, 0x12000
	s_nop 0
	v_add_co_u32_e64 v106, s[2:3], s2, v26
	v_mov_b32_e32 v5, s7
	s_nop 0
	v_addc_co_u32_e64 v107, s[2:3], 0, v27, s[2:3]
	s_mov_b32 s2, 0x1b000
	s_nop 0
	v_add_co_u32_e64 v108, s[2:3], s2, v26
	ds_read_b128 v[30:33], v5
	ds_read_b128 v[34:37], v5 offset:16
	ds_read2_b32 v[96:97], v5 offset0:8 offset1:20
	ds_read_b128 v[38:41], v5 offset:48
	ds_read_b128 v[42:45], v5 offset:64
	ds_read_b128 v[46:49], v5 offset:96
	ds_read_b128 v[50:53], v5 offset:112
	ds_read2_b32 v[98:99], v5 offset0:32 offset1:44
	ds_read_b128 v[54:57], v5 offset:144
	ds_read_b128 v[58:61], v5 offset:160
	ds_read_b128 v[62:65], v5 offset:192
	ds_read_b128 v[66:69], v5 offset:208
	ds_read2_b32 v[100:101], v5 offset0:56 offset1:68
	ds_read_b128 v[70:73], v5 offset:240
	ds_read_b128 v[74:77], v5 offset:256
	ds_read_b128 v[78:81], v5 offset:288
	ds_read_b128 v[82:85], v5 offset:304
	ds_read2_b32 v[102:103], v5 offset0:80 offset1:92
	ds_read_b128 v[86:89], v5 offset:336
	ds_read_b128 v[90:93], v5 offset:352
	v_addc_co_u32_e64 v109, s[2:3], 0, v27, s[2:3]
	s_mov_b32 s2, 0x24000
	s_nop 0
	v_add_co_u32_e64 v110, s[2:3], s2, v26
	s_waitcnt lgkmcnt(14)
	v_mov_b32_e32 v116, v33
	v_addc_co_u32_e64 v111, s[2:3], 0, v27, s[2:3]
	s_mov_b32 s2, 0x2d000
	s_nop 0
	v_add_co_u32_e64 v112, s[2:3], s2, v26
	v_mov_b32_e32 v118, v37
	s_nop 0
	v_addc_co_u32_e64 v113, s[2:3], 0, v27, s[2:3]
	s_mov_b32 s2, 0x36000
	s_nop 0
	v_add_co_u32_e64 v114, s[2:3], s2, v26
	v_mov_b32_e32 v120, v41
	s_nop 0
	v_addc_co_u32_e64 v115, s[2:3], 0, v27, s[2:3]
	s_mov_b32 s2, 0x3f000
	s_nop 0
	v_add_co_u32_e64 v26, s[2:3], s2, v26
	global_load_dwordx2 v[104:105], v[104:105], off
	s_nop 0
	global_load_dwordx2 v[106:107], v[106:107], off
	s_nop 0
	global_load_dwordx2 v[108:109], v[108:109], off
	s_nop 0
	global_load_dwordx2 v[110:111], v[110:111], off
	s_nop 0
	global_load_dwordx2 v[112:113], v[112:113], off
	s_nop 0
	global_load_dwordx2 v[114:115], v[114:115], off
	v_addc_co_u32_e64 v27, s[2:3], 0, v27, s[2:3]
	global_load_dwordx2 v[26:27], v[26:27], off
	v_mov_b32_e32 v122, v45
	v_mov_b32_e32 v124, v97
	v_mov_b32_e32 v126, v49
	s_waitcnt lgkmcnt(13)
	v_mov_b32_e32 v130, v53
	s_waitcnt lgkmcnt(11)
	v_mov_b32_e32 v132, v57
	s_waitcnt lgkmcnt(10)
	v_mov_b32_e32 v134, v61
	v_mov_b32_e32 v136, v99
	s_waitcnt lgkmcnt(9)
	v_mov_b32_e32 v138, v65
	s_waitcnt lgkmcnt(8)
	v_mov_b32_e32 v140, v69
	s_addk_i32 s7, 0x180
	s_waitcnt lgkmcnt(6)
	v_mov_b32_e32 v142, v73
	s_waitcnt lgkmcnt(5)
	v_mov_b32_e32 v144, v77
	v_mov_b32_e32 v146, v101
	s_add_u32 s10, s10, 0x48000
	s_waitcnt lgkmcnt(4)
	v_mov_b32_e32 v148, v81
	s_waitcnt lgkmcnt(3)
	v_mov_b32_e32 v150, v85
	s_addc_u32 s11, s11, 0
	s_add_u32 s98, s10, 0x48000
	s_addc_u32 s99, s11, 0
	s_cmp_lt_u32 s10, 0x438000
	s_cselect_b32 s98, s98, 0
	s_cselect_b32 s99, s99, 0
	v_lshl_add_u64 v[162:163], v[160:161], 0, s[98:99]
	global_load_dword v164, v[162:163], off
	s_waitcnt lgkmcnt(1)
	v_mov_b32_e32 v152, v89
	s_waitcnt lgkmcnt(0)
	v_mov_b32_e32 v154, v93
	v_mov_b32_e32 v156, v103
	s_cmp_eq_u32 s10, 0x480000
	s_waitcnt vmcnt(8)
	v_pk_fma_f32 v[10:11], v[94:95], v[30:31], v[10:11] op_sel_hi:[1,0,1]
	v_pk_fma_f32 v[12:13], v[94:95], v[30:31], v[12:13] op_sel:[0,1,0]
	v_pk_fma_f32 v[14:15], v[94:95], v[32:33], v[14:15] op_sel_hi:[1,0,1]
	v_pk_fma_f32 v[16:17], v[94:95], v[116:117], v[16:17] op_sel_hi:[1,0,1]
	v_pk_fma_f32 v[18:19], v[94:95], v[34:35], v[18:19] op_sel_hi:[1,0,1]
	v_pk_fma_f32 v[20:21], v[94:95], v[34:35], v[20:21] op_sel:[0,1,0]
	v_pk_fma_f32 v[22:23], v[94:95], v[36:37], v[22:23] op_sel_hi:[1,0,1]
	v_pk_fma_f32 v[24:25], v[94:95], v[118:119], v[24:25] op_sel_hi:[1,0,1]
	v_pk_fma_f32 v[8:9], v[94:95], v[96:97], v[8:9] op_sel_hi:[1,0,1]
	s_waitcnt vmcnt(7)
	v_pk_fma_f32 v[10:11], v[104:105], v[38:39], v[10:11] op_sel_hi:[1,0,1]
	v_pk_fma_f32 v[12:13], v[104:105], v[38:39], v[12:13] op_sel:[0,1,0]
	v_pk_fma_f32 v[14:15], v[104:105], v[40:41], v[14:15] op_sel_hi:[1,0,1]
	v_pk_fma_f32 v[16:17], v[104:105], v[120:121], v[16:17] op_sel_hi:[1,0,1]
	v_pk_fma_f32 v[18:19], v[104:105], v[42:43], v[18:19] op_sel_hi:[1,0,1]
	v_pk_fma_f32 v[20:21], v[104:105], v[42:43], v[20:21] op_sel:[0,1,0]
	v_pk_fma_f32 v[22:23], v[104:105], v[44:45], v[22:23] op_sel_hi:[1,0,1]
	v_pk_fma_f32 v[24:25], v[104:105], v[122:123], v[24:25] op_sel_hi:[1,0,1]
	v_pk_fma_f32 v[8:9], v[104:105], v[124:125], v[8:9] op_sel_hi:[1,0,1]
	s_waitcnt vmcnt(6)
	v_pk_fma_f32 v[10:11], v[106:107], v[46:47], v[10:11] op_sel_hi:[1,0,1]
	v_pk_fma_f32 v[12:13], v[106:107], v[46:47], v[12:13] op_sel:[0,1,0]
	v_pk_fma_f32 v[14:15], v[106:107], v[48:49], v[14:15] op_sel_hi:[1,0,1]
	v_pk_fma_f32 v[16:17], v[106:107], v[126:127], v[16:17] op_sel_hi:[1,0,1]
	v_pk_fma_f32 v[18:19], v[106:107], v[50:51], v[18:19] op_sel_hi:[1,0,1]
	v_pk_fma_f32 v[20:21], v[106:107], v[50:51], v[20:21] op_sel:[0,1,0]
	v_pk_fma_f32 v[22:23], v[106:107], v[52:53], v[22:23] op_sel_hi:[1,0,1]
	v_pk_fma_f32 v[24:25], v[106:107], v[130:131], v[24:25] op_sel_hi:[1,0,1]
	v_pk_fma_f32 v[8:9], v[106:107], v[98:99], v[8:9] op_sel_hi:[1,0,1]
	s_waitcnt vmcnt(5)
	v_pk_fma_f32 v[10:11], v[108:109], v[54:55], v[10:11] op_sel_hi:[1,0,1]
	v_pk_fma_f32 v[12:13], v[108:109], v[54:55], v[12:13] op_sel:[0,1,0]
	v_pk_fma_f32 v[14:15], v[108:109], v[56:57], v[14:15] op_sel_hi:[1,0,1]
	v_pk_fma_f32 v[16:17], v[108:109], v[132:133], v[16:17] op_sel_hi:[1,0,1]
	v_pk_fma_f32 v[18:19], v[108:109], v[58:59], v[18:19] op_sel_hi:[1,0,1]
	v_pk_fma_f32 v[20:21], v[108:109], v[58:59], v[20:21] op_sel:[0,1,0]
	v_pk_fma_f32 v[22:23], v[108:109], v[60:61], v[22:23] op_sel_hi:[1,0,1]
	v_pk_fma_f32 v[24:25], v[108:109], v[134:135], v[24:25] op_sel_hi:[1,0,1]
	v_pk_fma_f32 v[8:9], v[108:109], v[136:137], v[8:9] op_sel_hi:[1,0,1]
	s_waitcnt vmcnt(4)
	v_pk_fma_f32 v[10:11], v[110:111], v[62:63], v[10:11] op_sel_hi:[1,0,1]
	v_pk_fma_f32 v[12:13], v[110:111], v[62:63], v[12:13] op_sel:[0,1,0]
	v_pk_fma_f32 v[14:15], v[110:111], v[64:65], v[14:15] op_sel_hi:[1,0,1]
	v_pk_fma_f32 v[16:17], v[110:111], v[138:139], v[16:17] op_sel_hi:[1,0,1]
	v_pk_fma_f32 v[18:19], v[110:111], v[66:67], v[18:19] op_sel_hi:[1,0,1]
	v_pk_fma_f32 v[20:21], v[110:111], v[66:67], v[20:21] op_sel:[0,1,0]
	v_pk_fma_f32 v[22:23], v[110:111], v[68:69], v[22:23] op_sel_hi:[1,0,1]
	v_pk_fma_f32 v[24:25], v[110:111], v[140:141], v[24:25] op_sel_hi:[1,0,1]
	v_pk_fma_f32 v[8:9], v[110:111], v[100:101], v[8:9] op_sel_hi:[1,0,1]
	s_waitcnt vmcnt(3)
	v_pk_fma_f32 v[10:11], v[112:113], v[70:71], v[10:11] op_sel_hi:[1,0,1]
	v_pk_fma_f32 v[12:13], v[112:113], v[70:71], v[12:13] op_sel:[0,1,0]
	v_pk_fma_f32 v[14:15], v[112:113], v[72:73], v[14:15] op_sel_hi:[1,0,1]
	v_pk_fma_f32 v[16:17], v[112:113], v[142:143], v[16:17] op_sel_hi:[1,0,1]
	v_pk_fma_f32 v[18:19], v[112:113], v[74:75], v[18:19] op_sel_hi:[1,0,1]
	v_pk_fma_f32 v[20:21], v[112:113], v[74:75], v[20:21] op_sel:[0,1,0]
	v_pk_fma_f32 v[22:23], v[112:113], v[76:77], v[22:23] op_sel_hi:[1,0,1]
	v_pk_fma_f32 v[24:25], v[112:113], v[144:145], v[24:25] op_sel_hi:[1,0,1]
	v_pk_fma_f32 v[8:9], v[112:113], v[146:147], v[8:9] op_sel_hi:[1,0,1]
	s_waitcnt vmcnt(2)
	v_pk_fma_f32 v[10:11], v[114:115], v[78:79], v[10:11] op_sel_hi:[1,0,1]
	v_pk_fma_f32 v[12:13], v[114:115], v[78:79], v[12:13] op_sel:[0,1,0]
	v_pk_fma_f32 v[14:15], v[114:115], v[80:81], v[14:15] op_sel_hi:[1,0,1]
	v_pk_fma_f32 v[16:17], v[114:115], v[148:149], v[16:17] op_sel_hi:[1,0,1]
	v_pk_fma_f32 v[18:19], v[114:115], v[82:83], v[18:19] op_sel_hi:[1,0,1]
	v_pk_fma_f32 v[20:21], v[114:115], v[82:83], v[20:21] op_sel:[0,1,0]
	v_pk_fma_f32 v[22:23], v[114:115], v[84:85], v[22:23] op_sel_hi:[1,0,1]
	v_pk_fma_f32 v[24:25], v[114:115], v[150:151], v[24:25] op_sel_hi:[1,0,1]
	v_pk_fma_f32 v[8:9], v[114:115], v[102:103], v[8:9] op_sel_hi:[1,0,1]
	s_waitcnt vmcnt(1)
	v_pk_fma_f32 v[10:11], v[26:27], v[86:87], v[10:11] op_sel_hi:[1,0,1]
	v_pk_fma_f32 v[12:13], v[26:27], v[86:87], v[12:13] op_sel:[0,1,0]
	v_pk_fma_f32 v[14:15], v[26:27], v[88:89], v[14:15] op_sel_hi:[1,0,1]
	v_pk_fma_f32 v[16:17], v[26:27], v[152:153], v[16:17] op_sel_hi:[1,0,1]
	v_pk_fma_f32 v[18:19], v[26:27], v[90:91], v[18:19] op_sel_hi:[1,0,1]
	v_pk_fma_f32 v[20:21], v[26:27], v[90:91], v[20:21] op_sel:[0,1,0]
	v_pk_fma_f32 v[22:23], v[26:27], v[92:93], v[22:23] op_sel_hi:[1,0,1]
	v_pk_fma_f32 v[24:25], v[26:27], v[154:155], v[24:25] op_sel_hi:[1,0,1]
	v_pk_fma_f32 v[8:9], v[26:27], v[156:157], v[8:9] op_sel_hi:[1,0,1]
	s_cbranch_scc0 .LBB0_772
	s_waitcnt vmcnt(0)
	ds_write2st64_b64 v29, v[10:11], v[12:13] offset0:96 offset1:97
	ds_write2st64_b64 v29, v[14:15], v[16:17] offset0:98 offset1:99
	ds_write2st64_b64 v29, v[18:19], v[20:21] offset0:100 offset1:101
	ds_write2st64_b64 v29, v[22:23], v[24:25] offset0:102 offset1:103
	ds_write_b64 v29, v[8:9] offset:53248
	s_waitcnt lgkmcnt(0)
	s_barrier
	s_and_saveexec_b64 s[10:11], vcc
	s_cbranch_execz .LBB0_770
	s_mul_i32 s3, s6, 0x9000
	s_mul_hi_i32 s2, s6, 0x9000
	s_add_u32 s3, s14, s3
	s_addc_u32 s7, s15, s2
	s_add_u32 s2, s3, s8
	s_addc_u32 s3, s7, s9
	v_mov_b32_e32 v5, v129
	s_mul_hi_i32 s7, s6, 9
	s_mul_i32 s6, s6, 9
	v_lshl_add_u64 v[6:7], s[2:3], 0, v[4:5]
	v_lshl_add_u64 v[8:9], v[2:3], 0, s[8:9]
	s_mov_b64 s[8:9], 0
	v_mov_b32_e32 v5, v0
